# Griffin: gate loads waited at point of use (end of tile) instead of tile start
# speedup vs baseline: 1.0024x; 1.0024x over previous
.LBB0_484:
	s_cmp_lt_i32 s16, 0
	v_mov_b32_e32 v157, 0
	v_mov_b32_e32 v249, 0
	v_mov_b32_e32 v250, 0
	v_mov_b32_e32 v251, 0
	s_cbranch_scc1 .LBB0_486
	v_mov_b32_e32 v3, v233
	v_mov_b32_e32 v2, v232
	s_lshl_b32 s28, s16, 6
	s_add_u32 s28, s22, s28
	v_lshlrev_b32_e32 v4, 2, v3
	s_addc_u32 s29, s23, 0
	v_ashrrev_i32_e32 v5, 31, v4
	v_lshl_add_u64 v[4:5], s[28:29], 0, v[4:5]
	v_lshlrev_b64 v[4:5], 10, v[4:5]
	v_lshl_add_u64 v[4:5], s[24:25], 0, v[4:5]
	v_ashrrev_i32_e32 v3, 31, v2
	v_lshl_add_u64 v[2:3], v[2:3], 1, v[4:5]
	global_load_ushort v250, v[2:3], off offset:1024
	global_load_ushort v251, v[2:3], off
	global_load_ushort v157, v[2:3], off offset:3072
	global_load_ushort v249, v[2:3], off offset:2048

.LBB0_527:
	s_or_b64 exec, exec, s[28:29]
	v_mov_b32_e32 v75, v233
	v_mov_b32_e32 v76, v232
	s_lshl_b32 s16, s16, 6
	s_waitcnt lgkmcnt(0)
	s_barrier
	s_waitcnt vmcnt(0)
	v_lshlrev_b32_e32 v250, 16, v250
	v_lshlrev_b32_e32 v251, 16, v251
	v_lshlrev_b32_e32 v157, 16, v157
	v_lshlrev_b32_e32 v249, 16, v249
	s_add_u32 s28, s22, s16
	v_lshlrev_b32_e32 v78, 2, v75
	s_addc_u32 s29, s23, 0
	v_ashrrev_i32_e32 v79, 31, v78
	v_lshl_add_u64 v[78:79], s[28:29], 0, v[78:79]
	v_fma_f32 v68, v72, v74, v68
	v_lshlrev_b64 v[78:79], 11, v[78:79]
	v_mul_f32_e32 v72, v251, v68
	v_lshl_add_u64 v[78:79], s[26:27], 0, v[78:79]
	v_ashrrev_i32_e32 v77, 31, v76
	v_bfe_u32 v74, v72, 16, 1
	v_fmac_f32_e32 v69, v73, v68
	v_lshl_add_u64 v[76:77], v[76:77], 1, v[78:79]
	v_add3_u32 v72, v72, v74, s43
	v_mul_f32_e32 v68, v250, v69
	global_store_short_d16_hi v[76:77], v72, off
	v_bfe_u32 v72, v68, 16, 1
	v_add3_u32 v68, v68, v72, s43
	v_fma_f32 v66, v70, v69, v66
	global_store_short_d16_hi v[76:77], v68, off offset:2048
	v_mul_f32_e32 v68, v249, v66
	v_bfe_u32 v69, v68, 16, 1
	v_add3_u32 v70, v68, v69, s43
	v_add_co_u32_e32 v68, vcc, 0x1000, v76
	v_fmac_f32_e32 v67, v71, v66
	s_nop 0
	v_addc_co_u32_e32 v69, vcc, 0, v77, vcc
	v_mul_f32_e32 v66, v157, v67
	global_store_short_d16_hi v[68:69], v70, off
	v_bfe_u32 v70, v66, 16, 1
	v_add3_u32 v66, v66, v70, s43
	global_store_short_d16_hi v[68:69], v66, off offset:2048
	s_and_saveexec_b64 s[28:29], s[12:13]
	s_cbranch_execz .LBB0_482
	ds_write_b32 v239, v67 offset:20544
	s_branch .LBB0_482
